# split P6->P7 island barrier: arrive after P6, first-round diff attention units start without waiting, poll before first MLA unit
# speedup vs baseline: 1.0058x; 1.0053x over previous
.LBB0_901:
	v_mbcnt_lo_u32_b32 v0, -1, 0
	v_mbcnt_hi_u32_b32 v0, -1, v0
	s_waitcnt vmcnt(0)
	s_nop 0
	v_or_b32_e32 v0, s89, v0
	v_cmp_eq_u32_e32 vcc, 0, v0
	s_barrier
	s_and_saveexec_b64 s[0:1], vcc
	s_xor_b64 s[0:1], exec, s[0:1]
	s_cbranch_execz .LBB0_954
	s_add_i32 s2, 0, 0x22028
	v_mov_b32_e32 v0, s2
	s_waitcnt vmcnt(0) expcnt(0) lgkmcnt(0)
	ds_read_b32 v2, v0
	s_add_i32 s2, 0, 0x2202c
	v_mov_b32_e32 v0, s2
	ds_read_b32 v0, v0
	s_waitcnt lgkmcnt(0)
	v_readfirstlane_b32 s2, v2
	v_readfirstlane_b32 s3, v0
	s_mov_b32 s32, 1
	s_xor_b32 s2, s2, 32
	s_xor_b32 s3, s3, 1
	s_or_b32 s2, s2, s3
	s_cmp_lg_u32 s2, 0
	s_cbranch_scc1 .Lsplit_full
	v_readlane_b32 s2, v254, 8
	v_readlane_b32 s3, v254, 9
	s_lshl_b32 s4, s78, 8
	s_mov_b32 s32, 0
	s_add_u32 s2, s2, s4
	s_addc_u32 s3, s3, 0
	v_mov_b32_e32 v16, 0
	v_mov_b32_e32 v17, 1
	s_nop 1
	global_atomic_add v16, v17, s[2:3] offset:2048
	s_branch .LBB0_954
.Lsplit_full:
	s_waitcnt lgkmcnt(1)
	v_cmp_ne_u32_e32 vcc, 0, v2
	s_cbranch_vccnz .LBB0_917
	s_add_u32 s2, s66, 0x1000
	s_addc_u32 s3, s67, 0
	s_add_u32 s4, s66, 0x1100
	s_addc_u32 s5, s67, 0
	s_add_u32 s6, s66, 0x1200
	s_addc_u32 s7, s67, 0
	s_add_u32 s8, s66, 0x1300
	s_addc_u32 s9, s67, 0
	s_mov_b32 s10, 1
	v_mov_b32_e32 v16, 0
	s_branch .LBB0_905

.LBB0_960:
	s_or_b64 exec, exec, s[4:5]
	s_waitcnt vmcnt(0)
	v_readfirstlane_b32 s4, v2
	s_nop 1
	v_add_u32_e32 v0, s4, v0
	s_cmp_lt_u32 s4, 32
	s_cbranch_scc1 .Lsplit_done
	s_cmp_lg_u32 s32, 0
	s_cbranch_scc1 .Lsplit_done
	v_readlane_b32 s6, v255, 19
	v_readlane_b32 s7, v255, 20
	s_nop 4
.Lsplit_poll:
	global_load_dword v4, v1, s[6:7] offset:2048 sc1
	s_waitcnt vmcnt(0)
	v_readfirstlane_b32 s5, v4
	s_cmp_lt_u32 s5, 32
	s_cbranch_scc0 .Lsplit_got
	s_sleep 1
	s_branch .Lsplit_poll
.Lsplit_got:
	buffer_inv sc1
	s_waitcnt vmcnt(0)
	s_mov_b32 s32, 1
.Lsplit_done:
	s_add_i32 s4, s0, 0
	v_mov_b32_e32 v2, s4
	ds_write_b32 v2, v0
